# also keep the HGRN chunk-loop header waits from draining the previous chunk's two stores (vmcnt 1/0 -> 2), on top of the LRU/SSD wait counts
# speedup vs baseline: 1.0036x; 1.0036x over previous
; __device__ __forceinline__ float sigmoidf_(float x) { return __builtin_amdgcn_rcpf(1.0f + __expf(-x)); }
; __device__ __forceinline__ void hgrn_phase(const Args& A, unsigned char* smem, const bool dry) {
;     ...
;         float lbk[4];
; #pragma unroll
;         for (int c = 0; c < 4; ++c) lbk[c] = sigmoidf_(A.in[15][1024 + 128 * h + 4 * cq + c] - A.in[15][128 * h + 4 * cq + c]);
;         f32x4 Sacc[8];
; #pragma unroll
;         for (int j = 0; j < 8; ++j) Sacc[j] = (f32x4){0.f, 0.f, 0.f, 0.f};
;         __syncthreads();
;         for (int e = tid; e < 128 * 136 / 2; e += 512) ((unsigned*)Sb)[e] = 0u;
;         u32x2 frp[4], qrp[4]; u32x4 vp0, vp1;
;     ...
;         HG_ISSUE(0);
.LBB0_982:
	v_add_u32_e32 v5, 0x200, v5
	v_cmp_lt_u32_e32 vcc, s83, v5
	ds_write_b32 v4, v81
	s_or_b64 s[52:53], vcc, s[52:53]
	v_add_u32_e32 v4, 0x800, v4
	s_andn2_b64 exec, exec, s[52:53]
	s_cbranch_execnz .LBB0_982
	s_or_b64 exec, exec, s[52:53]
	s_bfe_u32 s63, s85, 0x10003
	s_cmp_eq_u32 s63, 0
	s_cselect_b64 s[52:53], -1, 0
	s_lshl_b32 s56, s85, 8
	v_cndmask_b32_e64 v4, v123, v114, s[52:53]
	s_and_b32 s68, s56, 0xfffff000
	s_lshl_b32 s78, s72, 1
	v_lshl_add_u64 v[84:85], v[82:83], 0, s[78:79]
	v_or_b32_e32 v4, s68, v4
	v_mad_i64_i32 v[4:5], s[64:65], v4, s84, v[84:85]
	v_cndmask_b32_e64 v8, v125, v124, s[52:53]
	s_lshl_b32 s64, s63, 11
	s_mov_b32 s65, s79
	v_or_b32_e32 v8, s68, v8
	v_lshl_add_u64 v[6:7], v[4:5], 0, s[64:65]
	v_mad_i64_i32 v[8:9], s[70:71], v8, s84, v[84:85]
	v_lshl_add_u64 v[10:11], v[8:9], 0, s[64:65]
	global_load_dwordx2 v[48:49], v[6:7], off offset:2048
	global_load_dwordx2 v[50:51], v[10:11], off offset:2048
	global_load_dwordx2 v[52:53], v[8:9], off
	global_load_dwordx2 v[54:55], v[4:5], off
	v_cndmask_b32_e64 v4, v127, v126, s[52:53]
	v_or_b32_e32 v4, s68, v4
	v_cndmask_b32_e64 v8, v129, v128, s[52:53]
	v_mad_i64_i32 v[4:5], s[70:71], v4, s84, v[84:85]
	v_or_b32_e32 v8, s68, v8
	v_lshl_add_u64 v[6:7], v[4:5], 0, s[64:65]
	v_mad_i64_i32 v[8:9], s[70:71], v8, s84, v[84:85]
	v_lshl_add_u64 v[10:11], v[8:9], 0, s[64:65]
	global_load_dwordx2 v[56:57], v[6:7], off offset:2048
	global_load_dwordx2 v[58:59], v[10:11], off offset:2048
	global_load_dwordx2 v[60:61], v[8:9], off
	global_load_dwordx2 v[62:63], v[4:5], off
	v_cndmask_b32_e64 v4, v115, v112, s[52:53]
	v_or_b32_e32 v6, s68, v4
	v_mov_b64_e32 v[4:5], s[96:97]
	v_mad_i64_i32 v[4:5], s[70:71], v6, s84, v[4:5]
	v_lshl_add_u64 v[4:5], v[4:5], 0, s[78:79]
	v_lshl_add_u64 v[4:5], v[4:5], 0, v[80:81]
	v_lshl_add_u64 v[6:7], v[4:5], 0, s[80:81]
	v_add_co_u32_e32 v4, vcc, s33, v4
	v_add_f32_e32 v0, 1.0, v0
	s_nop 0
	v_addc_co_u32_e32 v5, vcc, 0, v5, vcc
	global_load_dwordx4 v[32:35], v[4:5], off offset:2048
	global_load_dwordx4 v[36:39], v[6:7], off offset:16
	v_add_f32_e32 v1, 1.0, v1
	v_add_f32_e32 v2, 1.0, v2
	v_add_f32_e32 v3, 1.0, v3
	s_lshl_b32 s63, s63, 10
	v_rcp_f32_e32 v86, v0
	v_rcp_f32_e32 v87, v1
	v_rcp_f32_e32 v88, v2
	v_rcp_f32_e32 v89, v3
	s_add_u32 s64, s96, s64
	s_addc_u32 s65, s97, 0
	s_add_u32 s64, s64, s78
	s_addc_u32 s65, s65, 0
	v_mov_b32_e32 v0, 0
	s_mov_b32 s69, 0
	v_pk_add_f32 v[90:91], v[86:87], 1.0 op_sel_hi:[1,0] neg_lo:[1,0] neg_hi:[1,0]
	v_pk_add_f32 v[92:93], v[88:89], 1.0 op_sel_hi:[1,0] neg_lo:[1,0] neg_hi:[1,0]
	v_lshl_add_u64 v[94:95], s[64:65], 0, v[80:81]
	s_lshl_b32 s78, s63, 1
	s_lshl_b32 s62, s72, 1
	s_mov_b32 s70, 0
	v_mov_b32_e32 v1, v0
	v_mov_b32_e32 v2, v0
	v_mov_b32_e32 v3, v0
	v_mov_b32_e32 v4, v0
	v_mov_b32_e32 v5, v0
	v_mov_b32_e32 v6, v0
	v_mov_b32_e32 v7, v0
	v_mov_b32_e32 v8, v0
	v_mov_b32_e32 v9, v0
	v_mov_b32_e32 v10, v0
	v_mov_b32_e32 v11, v0
	v_mov_b32_e32 v12, v0
	v_mov_b32_e32 v13, v0
	v_mov_b32_e32 v14, v0
	v_mov_b32_e32 v15, v0
	v_mov_b32_e32 v16, v0
	v_mov_b32_e32 v17, v0
	v_mov_b32_e32 v18, v0
	v_mov_b32_e32 v19, v0
	v_mov_b32_e32 v20, v0
	v_mov_b32_e32 v21, v0
	v_mov_b32_e32 v22, v0
	v_mov_b32_e32 v23, v0
	v_mov_b32_e32 v24, v0
	v_mov_b32_e32 v25, v0
	v_mov_b32_e32 v26, v0
	v_mov_b32_e32 v27, v0
	v_mov_b32_e32 v28, v0
	v_mov_b32_e32 v29, v0
	v_mov_b32_e32 v30, v0
	v_mov_b32_e32 v31, v0
	s_waitcnt vmcnt(0)
	s_branch .LBB0_985

; __device__ __forceinline__ float bf_lo(unsigned w) { return __uint_as_float(w << 16); }
; __device__ __forceinline__ float bf_hi(unsigned w) { return __uint_as_float(w & 0xffff0000u); }
; __device__ __forceinline__ float sigmoidf_(float x) { return __builtin_amdgcn_rcpf(1.0f + __expf(-x)); }
; __device__ __forceinline__ void hgrn_phase(const Args& A, unsigned char* smem, const bool dry) {
;     ...
;             float Pl[4][4], kk[4][4];
;             { float P[4] = {1.0f, 1.0f, 1.0f, 1.0f};
; #pragma unroll
;                 for (int e = 0; e < 4; ++e) { const float fr[4] = {bf_lo(frp[e].x), bf_hi(frp[e].x), bf_lo(frp[e].y), bf_hi(frp[e].y)};
; #pragma unroll
;                     for (int c = 0; c < 4; ++c) { const float f = lbk[c] + (1.0f - lbk[c]) * sigmoidf_(fr[c]); P[c] *= f; Pl[e][c] = P[c]; kk[e][c] = 1.0f - f; } }
;                 *(f32x4*)(seg + tg * 128 + 4 * cq) = (f32x4){P[0], P[1], P[2], P[3]}; }
;             { *(u32x4*)(Vb + si * 136 + c16) = vp0; *(u32x4*)(Vb + si * 136 + c16 + 8) = vp1; }
;             __syncthreads();
;             { f32x4 pre = (f32x4){1.f, 1.f, 1.f, 1.f}, tot = pre;
; #pragma unroll
;                 for (int g2 = 0; g2 < 16; ++g2) { const f32x4 sv = *(const f32x4*)(seg + g2 * 128 + 4 * cq); tot = tot * sv; const f32x4 pv = pre * sv; pre = (g2 < tg) ? pv : pre; }
.LBB0_985:
	s_waitcnt vmcnt(9)
	v_lshlrev_b32_e32 v40, 16, v48
	v_and_b32_e32 v41, 0xffff0000, v48
	v_mul_f32_e32 v40, 0xbfb8aa3b, v40
	v_mul_f32_e32 v41, 0xbfb8aa3b, v41
	s_waitcnt vmcnt(8)
	v_lshlrev_b32_e32 v44, 16, v50
	v_and_b32_e32 v45, 0xffff0000, v50
	v_exp_f32_e32 v40, v40
	v_exp_f32_e32 v41, v41
	v_mul_f32_e32 v44, 0xbfb8aa3b, v44
	v_mul_f32_e32 v45, 0xbfb8aa3b, v45
	v_exp_f32_e32 v44, v44
	v_exp_f32_e32 v45, v45
	v_add_f32_e32 v40, 1.0, v40
	v_add_f32_e32 v41, 1.0, v41
	v_rcp_f32_e32 v40, v40
	v_rcp_f32_e32 v41, v41
	v_add_f32_e32 v44, 1.0, v44
	v_add_f32_e32 v45, 1.0, v45
	v_rcp_f32_e32 v44, v44
	v_rcp_f32_e32 v45, v45
	v_lshlrev_b32_e32 v42, 16, v49
	v_and_b32_e32 v43, 0xffff0000, v49
	v_lshlrev_b32_e32 v46, 16, v51
	v_and_b32_e32 v47, 0xffff0000, v51
	s_waitcnt vmcnt(4)
	v_lshlrev_b32_e32 v68, 16, v58
	v_mul_f32_e32 v42, 0xbfb8aa3b, v42
	v_mul_f32_e32 v43, 0xbfb8aa3b, v43
	v_mul_f32_e32 v46, 0xbfb8aa3b, v46
	v_mul_f32_e32 v47, 0xbfb8aa3b, v47
	v_lshlrev_b32_e32 v64, 16, v56
	v_and_b32_e32 v65, 0xffff0000, v56
	v_lshlrev_b32_e32 v66, 16, v57
	v_and_b32_e32 v67, 0xffff0000, v57
	v_and_b32_e32 v69, 0xffff0000, v58
	v_lshlrev_b32_e32 v74, 16, v59
	v_mul_f32_e32 v68, 0xbfb8aa3b, v68
	v_exp_f32_e32 v42, v42
	v_exp_f32_e32 v43, v43
	v_exp_f32_e32 v46, v46
	v_exp_f32_e32 v47, v47
	v_mul_f32_e32 v64, 0xbfb8aa3b, v64
	v_mul_f32_e32 v65, 0xbfb8aa3b, v65
	v_mul_f32_e32 v66, 0xbfb8aa3b, v66
	v_mul_f32_e32 v67, 0xbfb8aa3b, v67
	v_exp_f32_e32 v68, v68
	v_mul_f32_e32 v69, 0xbfb8aa3b, v69
	v_and_b32_e32 v75, 0xffff0000, v59
	v_pk_fma_f32 v[100:101], v[90:91], v[40:41], v[86:87]
	v_mul_f32_e32 v40, 0xbfb8aa3b, v74
	v_exp_f32_e32 v64, v64
	v_exp_f32_e32 v65, v65
	v_exp_f32_e32 v66, v66
	v_exp_f32_e32 v67, v67
	v_exp_f32_e32 v69, v69
	v_pk_fma_f32 v[76:77], v[90:91], v[44:45], v[86:87]
	v_exp_f32_e32 v44, v40
	v_mul_f32_e32 v40, 0xbfb8aa3b, v75
	v_exp_f32_e32 v45, v40
	v_add_f32_e32 v42, 1.0, v42
	v_add_f32_e32 v43, 1.0, v43
	v_add_f32_e32 v46, 1.0, v46
	v_add_f32_e32 v47, 1.0, v47
	v_add_f32_e32 v68, 1.0, v68
	v_rcp_f32_e32 v42, v42
	v_rcp_f32_e32 v43, v43
	v_rcp_f32_e32 v46, v46
	v_rcp_f32_e32 v47, v47
	v_add_f32_e32 v64, 1.0, v64
	v_add_f32_e32 v65, 1.0, v65
	v_add_f32_e32 v66, 1.0, v66
	v_add_f32_e32 v67, 1.0, v67
	v_rcp_f32_e32 v72, v68
	v_add_f32_e32 v68, 1.0, v69
	v_rcp_f32_e32 v64, v64
	v_rcp_f32_e32 v65, v65
	v_rcp_f32_e32 v66, v66
	v_rcp_f32_e32 v67, v67
	v_rcp_f32_e32 v73, v68
	v_add_f32_e32 v44, 1.0, v44
	v_add_f32_e32 v45, 1.0, v45
	v_rcp_f32_e32 v44, v44
	v_rcp_f32_e32 v45, v45
	v_pk_fma_f32 v[102:103], v[92:93], v[42:43], v[88:89]
	v_pk_fma_f32 v[96:97], v[92:93], v[46:47], v[88:89]
	v_pk_mul_f32 v[78:79], v[100:101], v[76:77]
	v_pk_fma_f32 v[68:69], v[90:91], v[64:65], v[86:87]
	v_pk_fma_f32 v[64:65], v[90:91], v[72:73], v[86:87]
	v_pk_mul_f32 v[98:99], v[102:103], v[96:97]
	v_pk_fma_f32 v[72:73], v[92:93], v[66:67], v[88:89]
	v_pk_mul_f32 v[70:71], v[78:79], v[68:69]
	v_pk_mul_f32 v[74:75], v[98:99], v[72:73]
	v_pk_fma_f32 v[66:67], v[92:93], v[44:45], v[88:89]
	v_pk_mul_f32 v[40:41], v[70:71], v[64:65]
	v_pk_mul_f32 v[42:43], v[74:75], v[66:67]
	ds_write_b128 v117, v[40:43]
	s_waitcnt vmcnt(2)
	ds_write_b128 v138, v[32:35] offset:52224
	s_waitcnt vmcnt(2)
	ds_write_b128 v138, v[36:39] offset:52240
	s_waitcnt lgkmcnt(0)
	s_barrier
	ds_read_b128 v[44:47], v116
	ds_read_b128 v[104:107], v116 offset:512
	v_pk_add_f32 v[76:77], v[76:77], 1.0 op_sel_hi:[1,0] neg_lo:[1,0] neg_hi:[1,0]
	v_pk_add_f32 v[96:97], v[96:97], 1.0 op_sel_hi:[1,0] neg_lo:[1,0] neg_hi:[1,0]
	v_pk_add_f32 v[68:69], v[68:69], 1.0 op_sel_hi:[1,0] neg_lo:[1,0] neg_hi:[1,0]
	s_waitcnt lgkmcnt(1)
	v_cndmask_b32_e64 v109, v47, 1.0, s[0:1]
	v_cndmask_b32_e64 v108, v46, 1.0, s[0:1]
	v_cndmask_b32_e64 v111, v45, 1.0, s[0:1]
	v_cndmask_b32_e64 v110, v44, 1.0, s[0:1]
	s_waitcnt lgkmcnt(0)
	v_pk_mul_f32 v[148:149], v[46:47], v[106:107]
	v_pk_mul_f32 v[150:151], v[44:45], v[104:105]
	ds_read_b128 v[44:47], v116 offset:1024
	v_pk_mul_f32 v[104:105], v[110:111], v[104:105]
	v_pk_mul_f32 v[106:107], v[108:109], v[106:107]
	v_cndmask_b32_e64 v111, v111, v105, s[4:5]
	v_cndmask_b32_e64 v109, v109, v107, s[4:5]
	v_cndmask_b32_e64 v108, v108, v106, s[4:5]
	v_cndmask_b32_e64 v110, v110, v104, s[4:5]
	ds_read_b128 v[104:107], v116 offset:1536
	s_waitcnt lgkmcnt(1)
	v_pk_mul_f32 v[148:149], v[148:149], v[46:47]
	v_pk_mul_f32 v[150:151], v[150:151], v[44:45]
	v_pk_mul_f32 v[44:45], v[44:45], v[110:111]
	v_pk_mul_f32 v[46:47], v[46:47], v[108:109]
	v_cndmask_b32_e64 v111, v111, v45, s[6:7]
	v_cndmask_b32_e64 v109, v109, v47, s[6:7]
	v_cndmask_b32_e64 v108, v108, v46, s[6:7]
	v_cndmask_b32_e64 v110, v110, v44, s[6:7]
	ds_read_b128 v[44:47], v116 offset:2048
	s_waitcnt lgkmcnt(1)
	v_pk_mul_f32 v[148:149], v[148:149], v[106:107]
	v_pk_mul_f32 v[150:151], v[150:151], v[104:105]
	v_pk_mul_f32 v[104:105], v[104:105], v[110:111]
	v_pk_mul_f32 v[106:107], v[106:107], v[108:109]
	v_cndmask_b32_e64 v111, v111, v105, s[8:9]
	v_cndmask_b32_e64 v109, v109, v107, s[8:9]
	v_cndmask_b32_e64 v108, v108, v106, s[8:9]
	v_cndmask_b32_e64 v110, v110, v104, s[8:9]
	ds_read_b128 v[104:107], v116 offset:2560
	s_waitcnt lgkmcnt(1)
	v_pk_mul_f32 v[148:149], v[148:149], v[46:47]
	v_pk_mul_f32 v[150:151], v[150:151], v[44:45]
	v_pk_mul_f32 v[44:45], v[44:45], v[110:111]
	v_pk_mul_f32 v[46:47], v[46:47], v[108:109]
	v_cndmask_b32_e64 v111, v111, v45, s[10:11]
	v_cndmask_b32_e64 v109, v109, v47, s[10:11]
	v_cndmask_b32_e64 v108, v108, v46, s[10:11]
	v_cndmask_b32_e64 v110, v110, v44, s[10:11]
	ds_read_b128 v[44:47], v116 offset:3072
	s_waitcnt lgkmcnt(1)
; __device__ __forceinline__ float bf_lo(unsigned w) { return __uint_as_float(w << 16); }
; __device__ __forceinline__ float bf_hi(unsigned w) { return __uint_as_float(w & 0xffff0000u); }
; __device__ __forceinline__ unsigned pk2(float lo, float hi) { const f32x2 v = (f32x2){lo, hi}; const bf16x2_t b = __builtin_convertvector(v, bf16x2_t); return __builtin_bit_cast(unsigned, b); }
; __device__ __forceinline__ void hgrn_phase(const Args& A, unsigned char* smem, const bool dry) {
;     ...
;             { f32x4 pre = (f32x4){1.f, 1.f, 1.f, 1.f}, tot = pre;
; #pragma unroll
;                 for (int g2 = 0; g2 < 16; ++g2) { const f32x4 sv = *(const f32x4*)(seg + g2 * 128 + 4 * cq); tot = tot * sv; const f32x4 pv = pre * sv; pre = (g2 < tg) ? pv : pre; }
; #pragma unroll
;                 for (int e = 0; e < 4; ++e) { const int i = 4 * tg + e; const float qv[4] = {bf_lo(qrp[e].x), bf_hi(qrp[e].x), bf_lo(qrp[e].y), bf_hi(qrp[e].y)};
;                     float oq[4], ok[4], ow[4];
; #pragma unroll
;                     for (int c = 0; c < 4; ++c) { const float Pc = Pl[e][c] * pre[c]; const float rP = __builtin_amdgcn_rcpf(Pc);
;                         oq[c] = qv[c] * 0.08838834764831845f * Pc; ok[c] = kk[e][c] * rP; ow[c] = kk[e][c] * tot[c] * rP; }
;                     u32x2 w; w.x = pk2(oq[0], oq[1]); w.y = pk2(oq[2], oq[3]); *(u32x2*)(Qt + i * 136 + 4 * cq) = w;
;                     w.x = pk2(ok[0], ok[1]); w.y = pk2(ok[2], ok[3]); *(u32x2*)(Kt + i * 136 + 4 * cq) = w;
;                     w.x = pk2(ow[0], ow[1]); w.y = pk2(ow[2], ow[3]); *(u32x2*)(Kw + i * 136 + 4 * cq) = w; }
	v_pk_mul_f32 v[148:149], v[148:149], v[106:107]
	v_pk_mul_f32 v[150:151], v[150:151], v[104:105]
	v_pk_mul_f32 v[104:105], v[104:105], v[110:111]
	v_pk_mul_f32 v[106:107], v[106:107], v[108:109]
	v_cndmask_b32_e64 v111, v111, v105, s[12:13]
	v_cndmask_b32_e64 v109, v109, v107, s[12:13]
	v_cndmask_b32_e64 v108, v108, v106, s[12:13]
	v_cndmask_b32_e64 v110, v110, v104, s[12:13]
	ds_read_b128 v[104:107], v116 offset:3584
	s_waitcnt lgkmcnt(1)
	v_pk_mul_f32 v[148:149], v[148:149], v[46:47]
	v_pk_mul_f32 v[150:151], v[150:151], v[44:45]
	v_pk_mul_f32 v[44:45], v[44:45], v[110:111]
	v_pk_mul_f32 v[46:47], v[46:47], v[108:109]
	v_cndmask_b32_e64 v111, v111, v45, s[14:15]
	v_cndmask_b32_e64 v109, v109, v47, s[14:15]
	v_cndmask_b32_e64 v108, v108, v46, s[14:15]
	v_cndmask_b32_e64 v110, v110, v44, s[14:15]
	ds_read_b128 v[44:47], v116 offset:4096
	s_waitcnt lgkmcnt(1)
	v_pk_mul_f32 v[148:149], v[148:149], v[106:107]
	v_pk_mul_f32 v[150:151], v[150:151], v[104:105]
	v_pk_mul_f32 v[104:105], v[104:105], v[110:111]
	v_pk_mul_f32 v[106:107], v[106:107], v[108:109]
	v_cndmask_b32_e64 v111, v111, v105, s[16:17]
	v_cndmask_b32_e64 v109, v109, v107, s[16:17]
	v_cndmask_b32_e64 v108, v108, v106, s[16:17]
	v_cndmask_b32_e64 v110, v110, v104, s[16:17]
	ds_read_b128 v[104:107], v116 offset:4608
	s_waitcnt lgkmcnt(1)
	v_pk_mul_f32 v[148:149], v[148:149], v[46:47]
	v_pk_mul_f32 v[150:151], v[150:151], v[44:45]
	v_pk_mul_f32 v[44:45], v[44:45], v[110:111]
	v_pk_mul_f32 v[46:47], v[46:47], v[108:109]
	v_cndmask_b32_e64 v111, v111, v45, s[18:19]
	v_cndmask_b32_e64 v109, v109, v47, s[18:19]
	v_cndmask_b32_e64 v108, v108, v46, s[18:19]
	v_cndmask_b32_e64 v110, v110, v44, s[18:19]
	ds_read_b128 v[44:47], v116 offset:5120
	s_waitcnt lgkmcnt(1)
	v_pk_mul_f32 v[148:149], v[148:149], v[106:107]
	v_pk_mul_f32 v[150:151], v[150:151], v[104:105]
	v_pk_mul_f32 v[104:105], v[104:105], v[110:111]
	v_pk_mul_f32 v[106:107], v[106:107], v[108:109]
	v_cndmask_b32_e64 v111, v111, v105, s[20:21]
	v_cndmask_b32_e64 v109, v109, v107, s[20:21]
	v_cndmask_b32_e64 v108, v108, v106, s[20:21]
	v_cndmask_b32_e64 v110, v110, v104, s[20:21]
	ds_read_b128 v[104:107], v116 offset:5632
	s_waitcnt lgkmcnt(1)
	v_pk_mul_f32 v[148:149], v[148:149], v[46:47]
	v_pk_mul_f32 v[150:151], v[150:151], v[44:45]
	v_pk_mul_f32 v[44:45], v[44:45], v[110:111]
	v_pk_mul_f32 v[46:47], v[46:47], v[108:109]
	v_cndmask_b32_e64 v111, v111, v45, s[22:23]
	v_cndmask_b32_e64 v109, v109, v47, s[22:23]
	v_cndmask_b32_e64 v108, v108, v46, s[22:23]
	v_cndmask_b32_e64 v110, v110, v44, s[22:23]
	ds_read_b128 v[44:47], v116 offset:6144
	s_waitcnt lgkmcnt(1)
	v_pk_mul_f32 v[148:149], v[148:149], v[106:107]
	v_pk_mul_f32 v[150:151], v[150:151], v[104:105]
	v_pk_mul_f32 v[104:105], v[104:105], v[110:111]
	v_pk_mul_f32 v[106:107], v[106:107], v[108:109]
	v_cndmask_b32_e64 v111, v111, v105, s[24:25]
	v_cndmask_b32_e64 v109, v109, v107, s[24:25]
	v_cndmask_b32_e64 v108, v108, v106, s[24:25]
	v_cndmask_b32_e64 v110, v110, v104, s[24:25]
	ds_read_b128 v[104:107], v116 offset:6656
	s_waitcnt lgkmcnt(1)
	v_pk_mul_f32 v[148:149], v[148:149], v[46:47]
	v_pk_mul_f32 v[150:151], v[150:151], v[44:45]
	v_pk_mul_f32 v[44:45], v[44:45], v[110:111]
	v_pk_mul_f32 v[46:47], v[46:47], v[108:109]
	v_cndmask_b32_e64 v111, v111, v45, s[26:27]
	v_cndmask_b32_e64 v109, v109, v47, s[26:27]
	v_cndmask_b32_e64 v108, v108, v46, s[26:27]
	v_cndmask_b32_e64 v110, v110, v44, s[26:27]
	ds_read_b128 v[44:47], v116 offset:7168
	s_waitcnt lgkmcnt(1)
	v_pk_mul_f32 v[148:149], v[148:149], v[106:107]
	v_pk_mul_f32 v[150:151], v[150:151], v[104:105]
	v_pk_mul_f32 v[104:105], v[104:105], v[110:111]
	v_pk_mul_f32 v[106:107], v[106:107], v[108:109]
	v_cndmask_b32_e64 v111, v111, v105, s[28:29]
	v_cndmask_b32_e64 v109, v109, v107, s[28:29]
	v_cndmask_b32_e64 v108, v108, v106, s[28:29]
	v_cndmask_b32_e64 v110, v110, v104, s[28:29]
	ds_read_b128 v[104:107], v116 offset:7680
	s_waitcnt lgkmcnt(1)
	v_pk_mul_f32 v[150:151], v[150:151], v[44:45]
	v_pk_mul_f32 v[44:45], v[44:45], v[110:111]
	v_pk_mul_f32 v[148:149], v[148:149], v[46:47]
	v_cndmask_b32_e64 v111, v111, v45, s[30:31]
	v_cndmask_b32_e64 v110, v110, v44, s[30:31]
	s_waitcnt lgkmcnt(0)
	v_pk_mul_f32 v[44:45], v[150:151], v[104:105]
	v_pk_mul_f32 v[104:105], v[104:105], v[110:111]
	v_pk_mul_f32 v[46:47], v[46:47], v[108:109]
	v_cndmask_b32_e64 v105, v111, v105, s[34:35]
	v_cndmask_b32_e64 v104, v110, v104, s[34:35]
	v_cndmask_b32_e64 v109, v109, v47, s[30:31]
	v_cndmask_b32_e64 v108, v108, v46, s[30:31]
	v_pk_mul_f32 v[110:111], v[100:101], v[104:105]
	v_pk_mul_f32 v[46:47], v[148:149], v[106:107]
	v_pk_mul_f32 v[106:107], v[106:107], v[108:109]
	v_rcp_f32_e32 v148, v110
	v_rcp_f32_e32 v149, v111
	v_cndmask_b32_e64 v107, v109, v107, s[34:35]
	v_cndmask_b32_e64 v106, v108, v106, s[34:35]
	v_lshlrev_b32_e32 v108, 16, v54
	v_and_b32_e32 v109, 0xffff0000, v54
	v_pk_mul_f32 v[150:151], v[102:103], v[106:107]
	v_pk_mul_f32 v[108:109], v[108:109], s[82:83] op_sel_hi:[1,0]
	v_pk_add_f32 v[100:101], v[100:101], 1.0 op_sel_hi:[1,0] neg_lo:[1,0] neg_hi:[1,0]
	v_rcp_f32_e32 v154, v150
	v_rcp_f32_e32 v155, v151
	v_pk_mul_f32 v[108:109], v[108:109], v[110:111]
	v_pk_mul_f32 v[110:111], v[100:101], v[148:149]
	v_pk_mul_f32 v[100:101], v[100:101], v[44:45]
	v_pk_add_f32 v[102:103], v[102:103], 1.0 op_sel_hi:[1,0] neg_lo:[1,0] neg_hi:[1,0]
	v_pk_mul_f32 v[100:101], v[100:101], v[148:149]
	v_lshlrev_b32_e32 v148, 16, v55
	v_and_b32_e32 v149, 0xffff0000, v55
	v_pk_mul_f32 v[148:149], v[148:149], s[82:83] op_sel_hi:[1,0]
	v_pk_mul_f32 v[78:79], v[78:79], v[104:105]
	v_pk_mul_f32 v[148:149], v[148:149], v[150:151]
; __device__ __forceinline__ float bf_lo(unsigned w) { return __uint_as_float(w << 16); }
; __device__ __forceinline__ float bf_hi(unsigned w) { return __uint_as_float(w & 0xffff0000u); }
; __device__ __forceinline__ unsigned pk2(float lo, float hi) { const f32x2 v = (f32x2){lo, hi}; const bf16x2_t b = __builtin_convertvector(v, bf16x2_t); return __builtin_bit_cast(unsigned, b); }
; __device__ __forceinline__ void hgrn_phase(const Args& A, unsigned char* smem, const bool dry) {
;     ...
;                 for (int e = 0; e < 4; ++e) { const int i = 4 * tg + e; const float qv[4] = {bf_lo(qrp[e].x), bf_hi(qrp[e].x), bf_lo(qrp[e].y), bf_hi(qrp[e].y)};
;                     float oq[4], ok[4], ow[4];
; #pragma unroll
;                     for (int c = 0; c < 4; ++c) { const float Pc = Pl[e][c] * pre[c]; const float rP = __builtin_amdgcn_rcpf(Pc);
;                         oq[c] = qv[c] * 0.08838834764831845f * Pc; ok[c] = kk[e][c] * rP; ow[c] = kk[e][c] * tot[c] * rP; }
;                     u32x2 w; w.x = pk2(oq[0], oq[1]); w.y = pk2(oq[2], oq[3]); *(u32x2*)(Qt + i * 136 + 4 * cq) = w;
;                     w.x = pk2(ok[0], ok[1]); w.y = pk2(ok[2], ok[3]); *(u32x2*)(Kt + i * 136 + 4 * cq) = w;
;                     w.x = pk2(ow[0], ow[1]); w.y = pk2(ow[2], ow[3]); *(u32x2*)(Kw + i * 136 + 4 * cq) = w; }
;                 if (tg == 0) *(f32x4*)(decv + 4 * cq) = tot; }
;             if (bt + 1 < 64) { HG_ISSUE(bt + 1); }
	v_pk_mul_f32 v[150:151], v[102:103], v[154:155]
	v_pk_mul_f32 v[102:103], v[102:103], v[46:47]
	v_cvt_pk_bf16_f32 v100, v100, v101
	v_pk_mul_f32 v[102:103], v[102:103], v[154:155]
	v_cvt_pk_bf16_f32 v108, v108, v109
	v_cvt_pk_bf16_f32 v101, v102, v103
	v_rcp_f32_e32 v102, v78
	v_rcp_f32_e32 v103, v79
	v_cvt_pk_bf16_f32 v109, v148, v149
	v_cvt_pk_bf16_f32 v110, v110, v111
	v_cvt_pk_bf16_f32 v111, v150, v151
	ds_write_b64 v130, v[100:101] offset:34816
	v_lshlrev_b32_e32 v100, 16, v52
	v_and_b32_e32 v101, 0xffff0000, v52
	v_pk_mul_f32 v[98:99], v[98:99], v[106:107]
	ds_write2st64_b64 v130, v[108:109], v[110:111] offset1:34
	v_pk_mul_f32 v[100:101], v[100:101], s[82:83] op_sel_hi:[1,0]
	v_rcp_f32_e32 v108, v98
	v_rcp_f32_e32 v109, v99
	v_pk_mul_f32 v[78:79], v[100:101], v[78:79]
	v_pk_mul_f32 v[100:101], v[76:77], v[102:103]
	v_pk_mul_f32 v[76:77], v[76:77], v[44:45]
	v_cvt_pk_bf16_f32 v78, v78, v79
	v_pk_mul_f32 v[76:77], v[76:77], v[102:103]
	v_lshlrev_b32_e32 v102, 16, v53
	v_and_b32_e32 v103, 0xffff0000, v53
	v_pk_mul_f32 v[102:103], v[102:103], s[82:83] op_sel_hi:[1,0]
	v_pk_mul_f32 v[70:71], v[70:71], v[104:105]
	v_pk_mul_f32 v[98:99], v[102:103], v[98:99]
	v_pk_mul_f32 v[102:103], v[96:97], v[108:109]
	v_pk_mul_f32 v[96:97], v[96:97], v[46:47]
	v_cvt_pk_bf16_f32 v79, v98, v99
	v_cvt_pk_bf16_f32 v98, v100, v101
	v_cvt_pk_bf16_f32 v99, v102, v103
	v_pk_mul_f32 v[96:97], v[96:97], v[108:109]
	ds_write2st64_b64 v131, v[78:79], v[98:99] offset1:34
	v_rcp_f32_e32 v78, v70
	v_rcp_f32_e32 v79, v71
	v_cvt_pk_bf16_f32 v76, v76, v77
	v_cvt_pk_bf16_f32 v77, v96, v97
	ds_write_b64 v131, v[76:77] offset:34816
	v_lshlrev_b32_e32 v76, 16, v62
	v_and_b32_e32 v77, 0xffff0000, v62
	v_pk_mul_f32 v[74:75], v[74:75], v[106:107]
	v_pk_mul_f32 v[76:77], v[76:77], s[82:83] op_sel_hi:[1,0]
	v_rcp_f32_e32 v96, v74
	v_rcp_f32_e32 v97, v75
	v_pk_mul_f32 v[70:71], v[76:77], v[70:71]
	v_pk_mul_f32 v[76:77], v[68:69], v[78:79]
	v_pk_mul_f32 v[68:69], v[68:69], v[44:45]
	v_pk_add_f32 v[72:73], v[72:73], 1.0 op_sel_hi:[1,0] neg_lo:[1,0] neg_hi:[1,0]
	v_pk_mul_f32 v[68:69], v[68:69], v[78:79]
	v_lshlrev_b32_e32 v78, 16, v63
	v_and_b32_e32 v79, 0xffff0000, v63
	v_pk_mul_f32 v[78:79], v[78:79], s[82:83] op_sel_hi:[1,0]
	v_cvt_pk_bf16_f32 v70, v70, v71
	v_pk_mul_f32 v[74:75], v[78:79], v[74:75]
	v_pk_mul_f32 v[78:79], v[72:73], v[96:97]
	v_pk_mul_f32 v[72:73], v[72:73], v[46:47]
	v_cvt_pk_bf16_f32 v71, v74, v75
	v_cvt_pk_bf16_f32 v74, v76, v77
	v_cvt_pk_bf16_f32 v75, v78, v79
	v_pk_mul_f32 v[40:41], v[40:41], v[104:105]
	v_pk_mul_f32 v[72:73], v[72:73], v[96:97]
	ds_write2st64_b64 v132, v[70:71], v[74:75] offset1:34
	v_rcp_f32_e32 v70, v40
	v_rcp_f32_e32 v71, v41
	v_cvt_pk_bf16_f32 v68, v68, v69
	v_cvt_pk_bf16_f32 v69, v72, v73
	ds_write_b64 v132, v[68:69] offset:34816
	v_lshlrev_b32_e32 v68, 16, v60
	v_and_b32_e32 v69, 0xffff0000, v60
	v_pk_mul_f32 v[42:43], v[42:43], v[106:107]
	v_pk_mul_f32 v[68:69], v[68:69], s[82:83] op_sel_hi:[1,0]
	v_pk_add_f32 v[64:65], v[64:65], 1.0 op_sel_hi:[1,0] neg_lo:[1,0] neg_hi:[1,0]
	v_rcp_f32_e32 v72, v42
	v_rcp_f32_e32 v73, v43
	v_pk_mul_f32 v[40:41], v[68:69], v[40:41]
	v_pk_mul_f32 v[68:69], v[64:65], v[70:71]
	v_pk_mul_f32 v[64:65], v[64:65], v[44:45]
	v_pk_add_f32 v[66:67], v[66:67], 1.0 op_sel_hi:[1,0] neg_lo:[1,0] neg_hi:[1,0]
	v_pk_mul_f32 v[64:65], v[64:65], v[70:71]
	v_lshlrev_b32_e32 v70, 16, v61
	v_and_b32_e32 v71, 0xffff0000, v61
	v_pk_mul_f32 v[70:71], v[70:71], s[82:83] op_sel_hi:[1,0]
	v_cvt_pk_bf16_f32 v40, v40, v41
	v_pk_mul_f32 v[42:43], v[70:71], v[42:43]
	v_pk_mul_f32 v[70:71], v[66:67], v[72:73]
	v_pk_mul_f32 v[66:67], v[66:67], v[46:47]
	v_cvt_pk_bf16_f32 v41, v42, v43
	v_pk_mul_f32 v[66:67], v[66:67], v[72:73]
	v_cvt_pk_bf16_f32 v42, v68, v69
	v_cvt_pk_bf16_f32 v43, v70, v71
	ds_write2st64_b64 v133, v[40:41], v[42:43] offset1:34
	v_cvt_pk_bf16_f32 v40, v64, v65
	v_cvt_pk_bf16_f32 v41, v66, v67
	ds_write_b64 v133, v[40:41] offset:34816
	s_and_saveexec_b64 s[64:65], s[0:1]
	ds_write_b128 v122, v[44:47]
	s_or_b64 exec, exec, s[64:65]
	s_mov_b64 s[64:65], -1
	s_cmpk_lg_i32 s70, 0xfc0
	v_add_u32_e32 v64, s69, v115
	v_add_u32_e32 v65, s70, v112
	s_cbranch_scc0 .LBB0_989
	v_add_u32_e32 v66, s70, v114
	v_add_u32_e32 v67, s69, v137
	v_add_u32_e32 v40, 64, v66
	v_add_u32_e32 v41, 0xfbf, v67
	v_cndmask_b32_e64 v40, v41, v40, s[52:53]
	v_add_u32_e32 v44, 0x41, v66
	v_add_u32_e32 v45, 0xfbe, v67
	v_add_u32_e32 v40, s68, v40
	v_cndmask_b32_e64 v44, v45, v44, s[52:53]
	v_mad_i64_i32 v[40:41], s[64:65], v40, s84, v[84:85]
	v_add_u32_e32 v44, s68, v44
	v_lshl_add_u64 v[42:43], v[40:41], 0, s[78:79]
	v_mad_i64_i32 v[44:45], s[64:65], v44, s84, v[84:85]
	v_lshl_add_u64 v[46:47], v[44:45], 0, s[78:79]
	global_load_dwordx2 v[96:97], v[42:43], off offset:2048
	global_load_dwordx2 v[98:99], v[46:47], off offset:2048
	global_load_dwordx2 v[100:101], v[44:45], off
	global_load_dwordx2 v[102:103], v[40:41], off
	v_add_u32_e32 v40, 0x42, v66
	v_add_u32_e32 v41, 0xfbd, v67
	v_cndmask_b32_e64 v40, v41, v40, s[52:53]
	v_add_u32_e32 v44, 0x43, v66
	v_add_u32_e32 v45, 0xfbc, v67
	v_add_u32_e32 v40, s68, v40
	v_cndmask_b32_e64 v44, v45, v44, s[52:53]
	v_mad_i64_i32 v[40:41], s[64:65], v40, s84, v[84:85]
	v_add_u32_e32 v44, s68, v44
	v_lshl_add_u64 v[42:43], v[40:41], 0, s[78:79]
	v_mad_i64_i32 v[44:45], s[64:65], v44, s84, v[84:85]
	v_add_u32_e32 v148, s69, v115
	v_add_u32_e32 v149, s70, v112
	v_lshl_add_u64 v[46:47], v[44:45], 0, s[78:79]
	global_load_dwordx2 v[104:105], v[42:43], off offset:2048
	global_load_dwordx2 v[106:107], v[46:47], off offset:2048
	global_load_dwordx2 v[108:109], v[44:45], off
	global_load_dwordx2 v[110:111], v[40:41], off
	v_subrev_u32_e32 v40, 64, v148
	v_add_u32_e32 v41, 64, v149
	v_cndmask_b32_e64 v40, v40, v41, s[52:53]
	v_add_u32_e32 v42, s68, v40
	v_mov_b64_e32 v[40:41], s[96:97]
	v_mad_i64_i32 v[40:41], s[64:65], v42, s84, v[40:41]
	s_mov_b32 s63, s79
	v_lshl_add_u64 v[40:41], v[40:41], 0, s[62:63]
	v_lshl_add_u64 v[40:41], v[40:41], 0, v[80:81]
	v_lshl_add_u64 v[42:43], v[40:41], 0, s[80:81]
	v_add_co_u32_e32 v40, vcc, 0x1000, v40
	s_mov_b64 s[64:65], 0
	s_nop 0
	v_addc_co_u32_e32 v41, vcc, 0, v41, vcc
	global_load_dwordx4 v[44:47], v[40:41], off offset:2048
	s_nop 0
	global_load_dwordx4 v[40:43], v[42:43], off offset:16
